# GLA chunk loop: output MFMA chain with all LDS fragment reads in flight (counted lgkmcnt)
# baseline (speedup 1.0000x reference)
; #define LAS __attribute__((address_space(3)))
; DI unsigned pk2(float lo, float hi) { return pg8::cvt_pk_bf16(lo, hi); }
; DI bf16 f2bf(float f) { return (bf16)(pk2(f, 0.f) & 0xffffu); }
; DI void gla_phase(const Ctx& C, const bf16* PROJ, const float* CUM, const bf16* PPG, const bf16* QH, const bf16* KH, bf16* OF, bf16* OB) {
;     ...
;             { const v4u k0 = tk[0], k1 = tk[1]; const v2u v = tv; LAS bf16* kt = KT + (16 * w) * LT + lane;
;                 kt[0 * LT] = (bf16)(k0.x & 0xffffu); kt[1 * LT] = (bf16)(k0.x >> 16); kt[2 * LT] = (bf16)(k0.y & 0xffffu); kt[3 * LT] = (bf16)(k0.y >> 16);
;                 kt[4 * LT] = (bf16)(k0.z & 0xffffu); kt[5 * LT] = (bf16)(k0.z >> 16); kt[6 * LT] = (bf16)(k0.w & 0xffffu); kt[7 * LT] = (bf16)(k0.w >> 16);
;                 kt[8 * LT] = (bf16)(k1.x & 0xffffu); kt[9 * LT] = (bf16)(k1.x >> 16); kt[10 * LT] = (bf16)(k1.y & 0xffffu); kt[11 * LT] = (bf16)(k1.y >> 16);
;                 kt[12 * LT] = (bf16)(k1.z & 0xffffu); kt[13 * LT] = (bf16)(k1.z >> 16); kt[14 * LT] = (bf16)(k1.w & 0xffffu); kt[15 * LT] = (bf16)(k1.w >> 16);
;                 LAS bf16* vt = VT + (4 * w) * LT + lane;
;                 vt[0 * LT] = (bf16)(v.x & 0xffffu); vt[1 * LT] = (bf16)(v.x >> 16); vt[2 * LT] = (bf16)(v.y & 0xffffu); vt[3 * LT] = (bf16)(v.y >> 16); }
;             if (c + 1 < SEQ / 64) GLA_LOAD(c + 1);
;             LBAR();
;             { const int tr = w >> 1, tc = w & 1;
;                 f32x4 acc = mm16<4>(Qh + 16 * tr * LQ, LQ, ST + 16 * tc * LQ, LQ, (f32x4){0.f, 0.f, 0.f, 0.f}, lane);
;                 acc = mm16<2>(Ps + 16 * tr * LT, LT, VT + 16 * tc * LT, LT, acc, lane);
; #pragma unroll
;                 for (int j = 0; j < 4; ++j) { const int t = 16 * tr + (lane >> 4) * 4 + j; OO[TOKOF(c, t) * 1024 + h * 256 + eb * 32 + 16 * tc + (lane & 15)] = f2bf(acc[j]); } }
; #pragma unroll
;             for (int ct = 0; ct < 2; ++ct) {
; #pragma unroll
;                 for (int j = 0; j < 4; ++j) Sacc[ct][j] *= etot[16 * w + (lane >> 4) * 4 + j];
;                 Sacc[ct] = mm16<2>(KT + 16 * w * LT, LT, VT + 16 * ct * LT, LT, Sacc[ct], lane); }
;             LBAR();
; #pragma unroll
;             for (int ct = 0; ct < 2; ++ct) { if (DBG_SKIP & 32) break; v2u o; o.x = pk2(Sacc[ct][0], Sacc[ct][1]); o.y = pk2(Sacc[ct][2], Sacc[ct][3]); *(LAS v2u*)(ST + (16 * ct + (lane & 15)) * LQ + 16 * w + (lane >> 4) * 4) = o; }
.LBB0_662:
	s_or_b64 exec, exec, s[0:1]
	ds_write_b16 v70, v14 offset:52224
	ds_write_b16_d16_hi v70, v14 offset:52368
	ds_write_b16 v70, v15 offset:52512
	ds_write_b16_d16_hi v70, v15 offset:52656
	ds_write_b16 v70, v16 offset:52800
	ds_write_b16_d16_hi v70, v16 offset:52944
	ds_write_b16 v70, v17 offset:53088
	ds_write_b16_d16_hi v70, v17 offset:53232
	ds_write_b16 v70, v22 offset:53376
	ds_write_b16_d16_hi v70, v22 offset:53520
	ds_write_b16 v70, v23 offset:53664
	ds_write_b16_d16_hi v70, v23 offset:53808
	ds_write_b16 v70, v24 offset:53952
	ds_write_b16_d16_hi v70, v24 offset:54096
	ds_write_b16 v70, v25 offset:54240
	ds_write_b16_d16_hi v70, v25 offset:54384
	ds_write_b16 v92, v56
	ds_write_b16_d16_hi v92, v56 offset:144
	ds_write_b16 v92, v57 offset:288
	ds_write_b16_d16_hi v92, v57 offset:432
	s_waitcnt lgkmcnt(0)
	s_barrier
	s_add_i32 s69, s69, s62
	s_add_i32 s67, s67, s16
	s_cmpk_gt_i32 s69, 0x7f
	ds_read_b128 v[124:127], v72 offset:17408
	ds_read_b128 v[128:131], v73
	ds_read_b128 v[132:135], v72 offset:17472
	ds_read_b128 v[136:139], v73 offset:64
	ds_read_b128 v[140:143], v72 offset:17536
	ds_read_b128 v[144:147], v73 offset:128
	ds_read_b128 v[164:167], v72 offset:17600
	ds_read_b128 v[168:171], v73 offset:192
	ds_read_b128 v[172:175], v74
	ds_read_b128 v[176:179], v75
	ds_read_b128 v[180:183], v74 offset:64
	ds_read_b128 v[184:187], v75 offset:64
	s_waitcnt lgkmcnt(10)
	v_mfma_f32_16x16x32_bf16 v[14:17], v[124:127], v[128:131], 0
	s_waitcnt lgkmcnt(8)
	v_mfma_f32_16x16x32_bf16 v[14:17], v[132:135], v[136:139], v[14:17]
	s_waitcnt lgkmcnt(6)
	v_mfma_f32_16x16x32_bf16 v[14:17], v[140:143], v[144:147], v[14:17]
	s_waitcnt lgkmcnt(4)
	v_mfma_f32_16x16x32_bf16 v[14:17], v[164:167], v[168:171], v[14:17]
	s_waitcnt lgkmcnt(2)
	v_mfma_f32_16x16x32_bf16 v[14:17], v[172:175], v[176:179], v[14:17]
	s_waitcnt lgkmcnt(0)
	v_mfma_f32_16x16x32_bf16 v[14:17], v[180:183], v[184:187], v[14:17]
	v_cndmask_b32_e64 v18, v81, v80, s[12:13]
	v_ashrrev_i32_e32 v19, 31, v18
	v_lshl_add_u64 v[18:19], s[30:31], 0, v[18:19]
	v_lshlrev_b64 v[18:19], 11, v[18:19]
	s_nop 3
	v_cvt_pk_bf16_f32 v14, v14, s0
	v_lshl_add_u64 v[18:19], v[54:55], 0, v[18:19]
	global_store_short v[18:19], v14, off
	v_cndmask_b32_e64 v14, v83, v82, s[12:13]
	v_cvt_pk_bf16_f32 v18, v15, s0
	v_ashrrev_i32_e32 v15, 31, v14
	v_lshl_add_u64 v[14:15], s[30:31], 0, v[14:15]
	v_lshlrev_b64 v[14:15], 11, v[14:15]
	v_lshl_add_u64 v[14:15], v[54:55], 0, v[14:15]
	global_store_short v[14:15], v18, off
	v_cndmask_b32_e64 v14, v85, v84, s[12:13]
	v_ashrrev_i32_e32 v15, 31, v14
	v_lshl_add_u64 v[14:15], s[30:31], 0, v[14:15]
	v_lshlrev_b64 v[14:15], 11, v[14:15]
	v_cvt_pk_bf16_f32 v16, v16, s0
	v_lshl_add_u64 v[14:15], v[54:55], 0, v[14:15]
	global_store_short v[14:15], v16, off
	v_cndmask_b32_e64 v14, v87, v86, s[12:13]
	v_ashrrev_i32_e32 v15, 31, v14
	v_lshl_add_u64 v[14:15], s[30:31], 0, v[14:15]
	v_lshlrev_b64 v[14:15], 11, v[14:15]
	v_cvt_pk_bf16_f32 v16, v17, s0
	v_lshl_add_u64 v[14:15], v[54:55], 0, v[14:15]
	global_store_short v[14:15], v16, off
	ds_read_b128 v[14:17], v78 offset:52224
	ds_read_b128 v[18:21], v78 offset:52288
	ds_read_b128 v[22:25], v79
	ds_read_b128 v[26:29], v79 offset:64
	ds_read_b128 v[30:33], v77
	s_waitcnt lgkmcnt(0)
	v_pk_mul_f32 v[8:9], v[8:9], v[32:33]
	v_pk_mul_f32 v[6:7], v[6:7], v[30:31]
	v_pk_mul_f32 v[12:13], v[12:13], v[32:33]
	v_pk_mul_f32 v[10:11], v[10:11], v[30:31]
	v_mfma_f32_16x16x32_bf16 v[6:9], v[14:17], v[22:25], v[6:9]
	ds_read_b128 v[22:25], v79 offset:2304
	s_waitcnt lgkmcnt(0)
	v_mfma_f32_16x16x32_bf16 v[10:13], v[14:17], v[22:25], v[10:13]
	ds_read_b128 v[14:17], v79 offset:2368
	s_waitcnt lgkmcnt(0)
	s_barrier
	v_mfma_f32_16x16x32_bf16 v[6:9], v[18:21], v[26:29], v[6:9]
	s_waitcnt lgkmcnt(0)
	v_mfma_f32_16x16x32_bf16 v[10:13], v[18:21], v[14:17], v[10:13]
	s_nop 5
	v_cvt_pk_bf16_f32 v6, v6, v7
	v_cvt_pk_bf16_f32 v7, v8, v9
	ds_write_b64 v93, v[6:7]
	v_cvt_pk_bf16_f32 v6, v10, v11
	v_cvt_pk_bf16_f32 v7, v12, v13
	ds_write_b64 v93, v[6:7] offset:4352
	s_waitcnt lgkmcnt(0)
	s_barrier
	s_cbranch_scc1 .LBB0_678

; DI bf16 f2bf(float f) { return (bf16)(pk2(f, 0.f) & 0xffffu); }
; #define LBAR() do { asm volatile("s_waitcnt lgkmcnt(0)" ::: "memory"); __builtin_amdgcn_s_barrier(); asm volatile("" ::: "memory"); } while (0)
; DI void gla_phase(const Ctx& C, const bf16* PROJ, const float* CUM, const bf16* PPG, const bf16* QH, const bf16* KH, bf16* OF, bf16* OB) {
;     ...
;             LBAR();
;             { const int tr = w >> 1, tc = w & 1;
;                 f32x4 acc = mm16<4>(Qh + 16 * tr * LQ, LQ, ST + 16 * tc * LQ, LQ, (f32x4){0.f, 0.f, 0.f, 0.f}, lane);
;                 acc = mm16<2>(Ps + 16 * tr * LT, LT, VT + 16 * tc * LT, LT, acc, lane);
; #pragma unroll
;                 for (int j = 0; j < 4; ++j) { const int t = 16 * tr + (lane >> 4) * 4 + j; OO[TOKOF(c, t) * 1024 + h * 256 + eb * 32 + 16 * tc + (lane & 15)] = f2bf(acc[j]); } }
.LBB0_671:
	s_or_b64 exec, exec, s[0:1]
	s_waitcnt lgkmcnt(0)
	s_barrier
	v_lshl_add_u64 v[66:67], v[66:67], 0, s[80:81]
	ds_read_b128 v[124:127], v72 offset:17408
	ds_read_b128 v[128:131], v73
	ds_read_b128 v[132:135], v72 offset:17472
	ds_read_b128 v[136:139], v73 offset:64
	ds_read_b128 v[140:143], v72 offset:17536
	ds_read_b128 v[144:147], v73 offset:128
	ds_read_b128 v[164:167], v72 offset:17600
	ds_read_b128 v[168:171], v73 offset:192
	ds_read_b128 v[172:175], v74
	ds_read_b128 v[176:179], v75
	ds_read_b128 v[180:183], v74 offset:64
	ds_read_b128 v[184:187], v75 offset:64
	s_waitcnt lgkmcnt(10)
	v_mfma_f32_16x16x32_bf16 v[96:99], v[124:127], v[128:131], 0
	s_waitcnt lgkmcnt(8)
	v_mfma_f32_16x16x32_bf16 v[96:99], v[132:135], v[136:139], v[96:99]
	s_waitcnt lgkmcnt(6)
	v_mfma_f32_16x16x32_bf16 v[96:99], v[140:143], v[144:147], v[96:99]
	s_waitcnt lgkmcnt(4)
	v_mfma_f32_16x16x32_bf16 v[96:99], v[164:167], v[168:171], v[96:99]
	s_waitcnt lgkmcnt(2)
	v_mfma_f32_16x16x32_bf16 v[96:99], v[172:175], v[176:179], v[96:99]
	s_waitcnt lgkmcnt(0)
	v_mfma_f32_16x16x32_bf16 v[96:99], v[180:183], v[184:187], v[96:99]
	v_add_u32_e32 v102, s42, v76
	v_add_u32_e32 v103, s43, v90
	v_add_u32_e32 v100, 0x7f, v103
	s_nop 4
	v_cvt_pk_bf16_f32 v95, v96, s0
	v_add_u32_e32 v96, 0xffffff81, v102
	v_cndmask_b32_e64 v100, v100, v96, s[12:13]
	v_ashrrev_i32_e32 v101, 31, v100
	v_lshl_add_u64 v[100:101], s[30:31], 0, v[100:101]
	v_lshlrev_b64 v[100:101], 11, v[100:101]
	v_lshl_add_u64 v[100:101], v[54:55], 0, v[100:101]
	global_store_short v[100:101], v95, off
	v_cvt_pk_bf16_f32 v95, v97, s0
	v_add_u32_e32 v96, 0xffffff82, v102
	v_add_u32_e32 v97, 0x7e, v103
	v_cndmask_b32_e64 v96, v97, v96, s[12:13]
	v_ashrrev_i32_e32 v97, 31, v96
	v_lshl_add_u64 v[96:97], s[30:31], 0, v[96:97]
	v_lshlrev_b64 v[96:97], 11, v[96:97]
	v_lshl_add_u64 v[96:97], v[54:55], 0, v[96:97]
	global_store_short v[96:97], v95, off
	v_add_u32_e32 v96, 0xffffff83, v102
	v_add_u32_e32 v97, 0x7d, v103
	v_cndmask_b32_e64 v96, v97, v96, s[12:13]
	v_ashrrev_i32_e32 v97, 31, v96
	v_lshl_add_u64 v[96:97], s[30:31], 0, v[96:97]
	v_lshlrev_b64 v[96:97], 11, v[96:97]
	v_cvt_pk_bf16_f32 v95, v98, s0
	v_lshl_add_u64 v[96:97], v[54:55], 0, v[96:97]
	global_store_short v[96:97], v95, off
	v_add_u32_e32 v96, 0xffffff84, v102
	v_add_u32_e32 v97, 0x7c, v103
	v_cndmask_b32_e64 v96, v97, v96, s[12:13]
	v_ashrrev_i32_e32 v97, 31, v96
	v_lshl_add_u64 v[96:97], s[30:31], 0, v[96:97]
	v_lshlrev_b64 v[96:97], 11, v[96:97]
	v_cvt_pk_bf16_f32 v95, v99, s0
	v_lshl_add_u64 v[96:97], v[54:55], 0, v[96:97]
	global_store_short v[96:97], v95, off
	ds_read_b128 v[96:99], v78 offset:52224
	ds_read_b128 v[100:103], v78 offset:52288
	ds_read_b128 v[104:107], v79
	ds_read_b128 v[108:111], v79 offset:64
	ds_read_b128 v[112:115], v77
	s_add_i32 s42, s42, 64
	s_sub_i32 s43, s43, 64
	s_mov_b64 s[0:1], 0x4000
	v_lshl_add_u64 v[60:61], v[60:61], 0, s[0:1]
	s_waitcnt lgkmcnt(0)
	v_pk_mul_f32 v[6:7], v[6:7], v[112:113]
	v_pk_mul_f32 v[8:9], v[8:9], v[114:115]
	v_pk_mul_f32 v[10:11], v[10:11], v[112:113]
	v_pk_mul_f32 v[12:13], v[12:13], v[114:115]
	v_mfma_f32_16x16x32_bf16 v[6:9], v[96:99], v[104:107], v[6:9]
	ds_read_b128 v[104:107], v79 offset:2304
	v_lshl_add_u64 v[62:63], v[62:63], 0, s[0:1]
	v_lshl_add_u64 v[64:65], v[64:65], 0, s[0:1]
	s_waitcnt lgkmcnt(0)
	v_mfma_f32_16x16x32_bf16 v[10:13], v[96:99], v[104:107], v[10:13]
	ds_read_b128 v[96:99], v79 offset:2368
	s_waitcnt lgkmcnt(0)
	s_barrier
	v_mfma_f32_16x16x32_bf16 v[6:9], v[100:103], v[108:111], v[6:9]
	s_cmpk_eq_i32 s42, 0x203f
	s_waitcnt lgkmcnt(0)
	v_mfma_f32_16x16x32_bf16 v[10:13], v[100:103], v[96:99], v[10:13]
	s_nop 4
	v_cvt_pk_bf16_f32 v96, v6, v7
	v_cvt_pk_bf16_f32 v97, v8, v9
	ds_write_b64 v93, v[96:97]
	v_cvt_pk_bf16_f32 v96, v10, v11
	v_cvt_pk_bf16_f32 v97, v12, v13
	ds_write_b64 v93, v[96:97] offset:4352
	s_cbranch_scc1 .LBB0_676
